# NSA tile loops: next K/V tile loaded HBM to LDS directly (global_load_lds_dwordx4) instead of VGPR staging plus ds_write at the end of the tile
# speedup vs baseline: 1.0269x; 1.0030x over previous
; #define NSA_LOADT(kb_, vb_, pitch_) do { int ln_ = lane; asm volatile("" : "+v"(ln_));   \
;         kreg = *(const u32x4*)((kb_) + (unsigned)(ln_ * (pitch_) + wid * 8)); vreg = *(const u32x4*)((vb_) + (unsigned)((16 * (wid & 3) + (ln_ >> 2)) * (pitch_) + (wid >> 2) * 32 + (ln_ & 3) * 8)); } while (0)
; __device__ __forceinline__ void nsa_unit(const Ctx& c, int l, int b, int n, int qt) {
;     ...
;             const bool more = rem != 0ull; int jn = 0;
;             if (more) { jn = __builtin_ctzll(rem); rem &= rem - 1; NSA_LOADT(Kb + (size_t)jn * 64 * HW, Vb + (size_t)jn * 64 * HW, HW); }
.LBB0_1323:
	s_cmp_eq_u64 s[2:3], 0
	s_cselect_b64 s[6:7], -1, 0
	s_cmp_lg_u64 s[2:3], 0
	s_mov_b64 s[4:5], 0
	s_cselect_b64 s[36:37], -1, 0
	s_and_b64 vcc, exec, s[6:7]
	s_mov_b32 s43, 0
	s_cbranch_vccnz .LBB0_1325
	s_flbit_i32_b64 s43, s[2:3]
	s_sub_i32 s43, 63, s43
	s_mov_b64 s[4:5], s[2:3]
	s_bitset0_b64 s[4:5], s43
	v_mov_b32_e32 v4, v247
	s_mul_i32 s2, s43, 0x70000
	s_add_u32 s2, s28, s2
	v_mul_lo_u32 v0, v4, s21
	s_addc_u32 s3, s29, 0
	s_add_u32 s2, s2, 0x600
	s_addc_u32 s3, s3, 0
	v_add_u32_e32 v0, s1, v0
	v_lshl_add_u64 v[2:3], v[0:1], 1, s[2:3]
	v_lshrrev_b32_e32 v0, 2, v4
	v_add_u32_e32 v0, s22, v0
	v_mul_lo_u32 v0, v0, s21
	s_add_u32 s2, s2, 0x100
	s_addc_u32 s3, s3, 0
	v_add_u32_e32 v0, s23, v0
	v_lshlrev_b32_e32 v4, 3, v4
	v_and_or_b32 v0, v4, 24, v0
	v_lshl_add_u64 v[4:5], v[0:1], 1, s[2:3]
	s_xor_b32 s9, s42, 1
	s_lshl_b32 s9, s9, 13
	s_add_i32 s9, s9, s26
	s_add_i32 m0, s9, 0x400
	s_nop 0
	global_load_lds_dwordx4 v[2:3], off
	s_add_i32 m0, s9, 0x4400
	s_nop 0
	global_load_lds_dwordx4 v[4:5], off

; #define NSA_STORET(slot_) do { *(LAS u32x4*)(lds + NL_KS + (slot_) * 8192 + wid * 1024 + lane * 16) = kreg; *(LAS u32x4*)(lds + NL_VS + (slot_) * 8192 + wid * 1024 + lane * 16) = vreg; } while (0)
; __device__ __forceinline__ void nsa_softmax_pv(NsaSm& st, f32x16& p0, f32x16& p1, const LAS unsigned char* vslot, LAS float* wsf, int lane, int r32, int hi, bool on = true) {
;     const float rmx = rowmax32(p0, p1); const float rm = on ? rmx : SNEG; const float mn = fmaxf(st.m, rm); const float f = __builtin_amdgcn_exp2f(st.m - mn); st.m = mn;
;     const float cs = on ? mn : 1.0e30f;
;     float s = 0.f;
; #pragma unroll
;     for (int r = 0; r < 16; ++r) { p0[r] = __builtin_amdgcn_exp2f(p0[r] - cs); p1[r] = __builtin_amdgcn_exp2f(p1[r] - cs); s += p0[r] + p1[r]; }
;     st.l = st.l * f + s;
; __device__ __forceinline__ void nsa_unit(const Ctx& c, int l, int b, int n, int qt) {
;     ...
;             if (more) NSA_STORET(cur ^ 1);
;             __syncthreads();
.LBB0_1335:
	v_pk_add_f32 v[80:81], v[80:81], v[82:83]
	v_pk_add_f32 v[84:85], v[84:85], v[86:87]
	v_pk_add_f32 v[88:89], v[88:89], v[90:91]
	v_pk_add_f32 v[92:93], v[92:93], v[94:95]
	v_pk_add_f32 v[128:129], v[128:129], v[130:131]
	v_pk_add_f32 v[132:133], v[132:133], v[134:135]
	v_pk_add_f32 v[136:137], v[136:137], v[138:139]
	v_pk_add_f32 v[140:141], v[140:141], v[142:143]
	v_pk_add_f32 v[80:81], v[80:81], v[84:85]
	v_pk_add_f32 v[88:89], v[88:89], v[92:93]
	v_pk_add_f32 v[128:129], v[128:129], v[132:133]
	v_pk_add_f32 v[136:137], v[136:137], v[140:141]
	v_pk_add_f32 v[80:81], v[80:81], v[88:89]
	v_pk_add_f32 v[128:129], v[128:129], v[136:137]
	v_pk_add_f32 v[80:81], v[80:81], v[128:129]
	v_add_f32_e32 v2, v80, v81
	v_fmac_f32_e32 v2, v157, v6
	s_andn2_b64 vcc, exec, s[6:7]
	s_xor_b32 s42, s42, 1
	s_waitcnt vmcnt(0) lgkmcnt(0)
	s_barrier
	s_cbranch_vccz .LBB0_1337
	v_mov_b32_e32 v157, v2
	v_mov_b32_e32 v158, v0
	s_mov_b32 s8, s43
	s_mov_b64 s[2:3], s[4:5]
	s_branch .LBB0_1323

; #define NSA_LOADT(kb_, vb_, pitch_) do { int ln_ = lane; asm volatile("" : "+v"(ln_));   \
;         kreg = *(const u32x4*)((kb_) + (unsigned)(ln_ * (pitch_) + wid * 8)); vreg = *(const u32x4*)((vb_) + (unsigned)((16 * (wid & 3) + (ln_ >> 2)) * (pitch_) + (wid >> 2) * 32 + (ln_ & 3) * 8)); } while (0)
; __device__ __forceinline__ void nsa_unit(const Ctx& c, int l, int b, int n, int qt) {
;     ...
;             const bool more = kt > klast;
;             if (more) NSA_LOADT(Kb + (size_t)(kt - 1) * 64 * HW, Vb + (size_t)(kt - 1) * 64 * HW, HW);
.LBB0_1340:
	s_add_i32 s19, s13, 1
	s_cmp_gt_i32 s19, s20
	s_cselect_b64 s[16:17], -1, 0
	s_cmp_le_i32 s19, s20
	s_cbranch_scc1 .LBB0_1342
	v_mov_b32_e32 v4, v247
	s_mul_i32 s8, s13, 0x70000
	s_mul_hi_u32 s9, s13, 0x70000
	s_add_u32 s8, s28, s8
	v_mul_lo_u32 v0, v4, s21
	s_addc_u32 s9, s29, s9
	s_add_u32 s8, s8, 0x800
	s_addc_u32 s9, s9, 0
	v_add_u32_e32 v0, s1, v0
	v_lshl_add_u64 v[2:3], v[0:1], 1, s[8:9]
	v_lshrrev_b32_e32 v0, 2, v4
	v_add_u32_e32 v0, s22, v0
	v_mul_lo_u32 v0, v0, s21
	s_add_u32 s8, s8, 0x100
	s_addc_u32 s9, s9, 0
	v_add_u32_e32 v0, s23, v0
	v_lshlrev_b32_e32 v4, 3, v4
	v_and_or_b32 v0, v4, 24, v0
	v_lshl_add_u64 v[4:5], v[0:1], 1, s[8:9]
	s_xor_b32 s8, s25, 1
	s_lshl_b32 s8, s8, 13
	s_add_i32 s8, s8, s26
	s_add_i32 m0, s8, 0x400
	s_nop 0
	global_load_lds_dwordx4 v[2:3], off
	s_add_i32 m0, s8, 0x4400
	s_nop 0
	global_load_lds_dwordx4 v[4:5], off

; #define NSA_STORET(slot_) do { *(LAS u32x4*)(lds + NL_KS + (slot_) * 8192 + wid * 1024 + lane * 16) = kreg; *(LAS u32x4*)(lds + NL_VS + (slot_) * 8192 + wid * 1024 + lane * 16) = vreg; } while (0)
; __device__ __forceinline__ void nsa_unit(const Ctx& c, int l, int b, int n, int qt) {
;     ...
;             nsa_softmax_pv(st, p0, p1, lds + NL_VS + cur * 8192, wsf, lane, r32, hi);
;             if (more) NSA_STORET(cur ^ 1);
;             __syncthreads();
;             if (!more) break;
;     ...
;         }
.LBB0_1352:
	v_pk_add_f32 v[128:129], v[128:129], v[130:131]
	v_pk_add_f32 v[132:133], v[132:133], v[134:135]
	v_pk_add_f32 v[136:137], v[136:137], v[138:139]
	v_pk_add_f32 v[140:141], v[140:141], v[142:143]
	v_pk_add_f32 v[112:113], v[112:113], v[114:115]
	v_pk_add_f32 v[116:117], v[116:117], v[118:119]
	v_pk_add_f32 v[120:121], v[120:121], v[122:123]
	v_pk_add_f32 v[124:125], v[124:125], v[126:127]
	v_pk_add_f32 v[128:129], v[128:129], v[132:133]
	v_pk_add_f32 v[136:137], v[136:137], v[140:141]
	v_pk_add_f32 v[112:113], v[112:113], v[116:117]
	v_pk_add_f32 v[120:121], v[120:121], v[124:125]
	v_pk_add_f32 v[128:129], v[128:129], v[136:137]
	v_pk_add_f32 v[112:113], v[112:113], v[120:121]
	v_pk_add_f32 v[128:129], v[128:129], v[112:113]
	v_add_f32_e32 v3, v128, v129
	s_xor_b32 s25, s25, 1
	s_add_i32 s13, s13, -1
	s_add_i32 s24, s24, 64
	v_fmac_f32_e32 v3, v250, v2
	s_cmp_gt_i32 s19, s20
	s_waitcnt vmcnt(0) lgkmcnt(0)
	s_barrier
	s_cbranch_scc0 .LBB0_1354
	v_mov_b32_e32 v250, v3
	v_mov_b32_e32 v233, v0
	s_branch .LBB0_1340
